# in-proj and gate/up GEMM unit loops: next-unit decode (StaticOrder next) moved from the unit head into the peeled first K-iteration's load segment
# speedup vs baseline: 1.0175x; 1.0043x over previous
.LBB0_255:
	s_add_u32 s88, s8, 0x100
	s_addc_u32 s89, s9, 0
	s_add_u32 s8, s38, 0x40080
	s_addc_u32 s9, s39, 0
	s_mov_b32 s90, -2
	s_add_u32 s38, s8, 0xfffc0080
	s_addc_u32 s39, s9, -1
	s_add_i32 s91, 0, 0x10000
	s_cmp_eq_u32 s90, 12
	s_cselect_b32 s57, s31, s39
	s_cselect_b32 s56, s47, s38
	s_cselect_b32 s39, s29, s89
	s_cselect_b32 s38, s87, s88
	s_add_i32 s94, 0, 0x14000
	v_add_u32_e32 v140, s91, v183
	v_add_u32_e32 v168, s94, v183
	ds_read_b128 v[128:131], v140
	ds_read_b128 v[132:135], v140 offset:1024
	ds_read_b128 v[136:139], v140 offset:2048
	ds_read_b128 v[140:143], v140 offset:3072
	ds_read_b128 v[144:147], v168
	ds_read_b128 v[148:151], v168 offset:1024
	ds_read_b128 v[164:167], v168 offset:2048
	ds_read_b128 v[168:171], v168 offset:3072
	v_lshl_add_u64 v[184:185], s[8:9], 0, v[162:163]
	s_add_i32 m0, s55, 0xc000
	ds_read_b128 v[172:175], v187
	ds_read_b128 v[176:179], v187 offset:1024
	ds_read_b128 v[188:191], v187 offset:2048
	ds_read_b128 v[202:205], v187 offset:3072
	ds_read_b128 v[206:209], v187 offset:4096
	ds_read_b128 v[210:213], v187 offset:5120
	ds_read_b128 v[214:217], v187 offset:6144
	ds_read_b128 v[218:221], v187 offset:7168
	global_load_lds_dwordx4 v[184:185], off
	v_lshl_add_u64 v[184:185], s[8:9], 0, v[160:161]
	s_add_i32 m0, s55, 0xe000
	s_nop 0
	global_load_lds_dwordx4 v[184:185], off
	s_add_i32 s85, s85, 1
	s_mul_i32 s6, s85, s43
	s_mul_hi_u32 s7, s85, s42
	s_add_i32 s7, s7, s6
	s_mul_i32 s6, s85, s42
	s_add_u32 s34, s6, s2
	s_addc_u32 s35, s7, s41
	v_mov_b64_e32 v[0:1], 0xf00
	v_cmp_lt_i64_e64 s[6:7], s[34:35], v[0:1]
	v_mov_b64_e32 v[0:1], 0xeff
	v_cmp_gt_i64_e32 vcc, s[34:35], v[0:1]
	s_cbranch_vccnz .LBB0_257
	s_ashr_i32 s28, s34, 31
	s_lshr_b32 s28, s28, 29
	s_add_i32 s28, s34, s28
	s_ashr_i32 s29, s28, 3
	s_and_b32 s28, s28, -8
	s_sub_i32 s28, s34, s28
	s_cmp_lt_i32 s28, 0
	s_movk_i32 s30, 0x1e1
	s_cselect_b32 s30, s30, 0x1e0
	s_mul_i32 s28, s28, s30
	s_add_i32 s28, s28, s29
	s_mul_hi_i32 s29, s28, 0x88888889
	s_add_i32 s29, s29, s28
	s_lshr_b32 s30, s29, 31
	s_ashr_i32 s29, s29, 6
	s_add_i32 s29, s29, s30
	s_lshl_b32 s30, s29, 3
	s_sub_i32 s31, 0x100, s30
	s_min_i32 s31, s31, 8
	s_abs_i32 s34, s31
	v_cvt_f32_u32_e32 v0, s34
	s_sub_i32 s36, 0, s34
	s_mulk_i32 s29, 0x78
	s_sub_i32 s29, s28, s29
	v_rcp_iflag_f32_e32 v0, v0
	s_abs_i32 s28, s29
	s_xor_b32 s35, s29, s31
	s_ashr_i32 s35, s35, 31
	v_mul_f32_e32 v0, 0x4f7ffffe, v0
	v_cvt_u32_f32_e32 v0, v0
	s_nop 0
	v_readfirstlane_b32 s37, v0
	s_mul_i32 s36, s36, s37
	s_mul_hi_u32 s36, s37, s36
	s_add_i32 s37, s37, s36
	s_mul_hi_u32 s36, s28, s37
	s_mul_i32 s37, s36, s34
	s_sub_i32 s28, s28, s37
	s_add_i32 s47, s36, 1
	s_sub_i32 s37, s28, s34
	s_cmp_ge_u32 s28, s34
	s_cselect_b32 s36, s47, s36
	s_cselect_b32 s28, s37, s28
	s_add_i32 s37, s36, 1
	s_cmp_ge_u32 s28, s34
	s_cselect_b32 s28, s37, s36
	s_xor_b32 s28, s28, s35
	s_sub_i32 s28, s28, s35
	s_mul_i32 s31, s28, s31
	s_sub_i32 s29, s29, s31
	s_add_i32 s30, s30, s29
.LBB0_257:
	s_ashr_i32 s31, s30, 31
	s_lshl_b64 s[34:35], s[30:31], 19
	s_add_u32 s34, s48, s34
	s_addc_u32 s35, s49, s35
	s_and_b64 s[36:37], s[6:7], exec
	s_cselect_b32 s31, s35, s57
	s_cselect_b32 s47, s34, s56
	s_ashr_i32 s29, s28, 31
	s_lshl_b64 s[36:37], s[28:29], 19
	s_add_u32 s36, s50, s36
	s_addc_u32 s37, s51, s37
	s_and_b64 s[100:101], s[6:7], exec
	s_cselect_b32 s29, s37, s89
	s_cselect_b32 s87, s36, s88
	s_waitcnt vmcnt(8)
	s_waitcnt lgkmcnt(0)
	s_barrier
	s_setprio 1
	s_waitcnt lgkmcnt(0)
	v_mfma_f32_16x16x32_bf16 v[124:127], v[128:131], v[172:175], 0
	v_mfma_f32_16x16x32_bf16 v[120:123], v[136:139], v[172:175], 0
	v_mfma_f32_16x16x32_bf16 v[112:115], v[128:131], v[188:191], 0
	v_mfma_f32_16x16x32_bf16 v[104:107], v[136:139], v[188:191], 0
	v_mfma_f32_16x16x32_bf16 v[96:99], v[128:131], v[206:209], 0
	v_mfma_f32_16x16x32_bf16 v[88:91], v[136:139], v[206:209], 0
	v_mfma_f32_16x16x32_bf16 v[80:83], v[128:131], v[214:217], 0
	v_mfma_f32_16x16x32_bf16 v[72:75], v[136:139], v[214:217], 0
	v_mfma_f32_16x16x32_bf16 v[124:127], v[132:135], v[176:179], v[124:127]
	v_mfma_f32_16x16x32_bf16 v[120:123], v[140:143], v[176:179], v[120:123]
	v_mfma_f32_16x16x32_bf16 v[112:115], v[132:135], v[202:205], v[112:115]
	v_mfma_f32_16x16x32_bf16 v[104:107], v[140:143], v[202:205], v[104:107]
	v_mfma_f32_16x16x32_bf16 v[96:99], v[132:135], v[210:213], v[96:99]
	v_mfma_f32_16x16x32_bf16 v[88:91], v[140:143], v[210:213], v[88:91]
	v_mfma_f32_16x16x32_bf16 v[80:83], v[132:135], v[218:221], v[80:83]
	v_mfma_f32_16x16x32_bf16 v[72:75], v[140:143], v[218:221], v[72:75]
	s_setprio 0
	s_setprio 1
	v_mfma_f32_16x16x32_bf16 v[116:119], v[144:147], v[172:175], 0
	v_mfma_f32_16x16x32_bf16 v[108:111], v[164:167], v[172:175], 0
	v_mfma_f32_16x16x32_bf16 v[100:103], v[144:147], v[188:191], 0
	v_mfma_f32_16x16x32_bf16 v[92:95], v[164:167], v[188:191], 0
	v_mfma_f32_16x16x32_bf16 v[84:87], v[144:147], v[206:209], 0
	v_mfma_f32_16x16x32_bf16 v[76:79], v[164:167], v[206:209], 0
	v_mfma_f32_16x16x32_bf16 v[68:71], v[144:147], v[214:217], 0
	v_mfma_f32_16x16x32_bf16 v[64:67], v[164:167], v[214:217], 0
	v_mfma_f32_16x16x32_bf16 v[116:119], v[148:151], v[176:179], v[116:119]
	v_mfma_f32_16x16x32_bf16 v[108:111], v[168:171], v[176:179], v[108:111]
	v_mfma_f32_16x16x32_bf16 v[100:103], v[148:151], v[202:205], v[100:103]
	v_mfma_f32_16x16x32_bf16 v[92:95], v[168:171], v[202:205], v[92:95]
	v_mfma_f32_16x16x32_bf16 v[84:87], v[148:151], v[210:213], v[84:87]
	v_mfma_f32_16x16x32_bf16 v[76:79], v[168:171], v[210:213], v[76:79]
	v_mfma_f32_16x16x32_bf16 v[68:71], v[148:151], v[218:221], v[68:71]
	v_mfma_f32_16x16x32_bf16 v[64:67], v[168:171], v[218:221], v[64:67]
	s_setprio 0
	s_barrier
	s_add_i32 s91, s91, s54
	v_lshl_add_u64 v[184:185], s[38:39], 0, v[192:193]
	s_mov_b32 m0, s91
	ds_read_b128 v[172:175], v187 offset:16384
	ds_read_b128 v[176:179], v187 offset:17408
	ds_read_b128 v[188:191], v187 offset:18432
	ds_read_b128 v[202:205], v187 offset:19456
	ds_read_b128 v[206:209], v187 offset:20480
	ds_read_b128 v[210:213], v187 offset:21504
	ds_read_b128 v[214:217], v187 offset:22528
	ds_read_b128 v[218:221], v187 offset:23552
	global_load_lds_dwordx4 v[184:185], off
	s_add_i32 m0, s91, 0x2000
	s_add_u32 s92, s38, 0x40000
	v_lshl_add_u64 v[222:223], s[38:39], 0, v[152:153]
	s_addc_u32 s93, s39, 0
	s_add_i32 s91, s94, s54
	global_load_lds_dwordx4 v[222:223], off
	v_lshl_add_u64 v[224:225], s[92:93], 0, v[192:193]
	s_mov_b32 m0, s91
	v_lshl_add_u64 v[226:227], s[56:57], 0, v[154:155]
	global_load_lds_dwordx4 v[224:225], off
	v_lshl_add_u64 v[224:225], s[92:93], 0, v[152:153]
	s_add_i32 m0, s91, 0x2000
	s_nop 0
	global_load_lds_dwordx4 v[224:225], off
	v_lshl_add_u64 v[224:225], s[56:57], 0, v[156:157]
	s_mov_b32 m0, s55
	s_nop 0
	global_load_lds_dwordx4 v[224:225], off
	s_mov_b32 m0, s60
	s_nop 0
	global_load_lds_dwordx4 v[226:227], off
	s_waitcnt vmcnt(8)
	s_waitcnt lgkmcnt(0)
	s_barrier
	s_setprio 1
	s_waitcnt lgkmcnt(0)
	v_mfma_f32_16x16x32_bf16 v[60:63], v[128:131], v[172:175], 0
	v_mfma_f32_16x16x32_bf16 v[56:59], v[136:139], v[172:175], 0
	v_mfma_f32_16x16x32_bf16 v[48:51], v[128:131], v[188:191], 0
	v_mfma_f32_16x16x32_bf16 v[40:43], v[136:139], v[188:191], 0
	v_mfma_f32_16x16x32_bf16 v[32:35], v[128:131], v[206:209], 0
	v_mfma_f32_16x16x32_bf16 v[24:27], v[136:139], v[206:209], 0
	v_mfma_f32_16x16x32_bf16 v[16:19], v[128:131], v[214:217], 0
	v_mfma_f32_16x16x32_bf16 v[8:11], v[136:139], v[214:217], 0
	v_mfma_f32_16x16x32_bf16 v[60:63], v[132:135], v[176:179], v[60:63]
	v_mfma_f32_16x16x32_bf16 v[56:59], v[140:143], v[176:179], v[56:59]
	v_mfma_f32_16x16x32_bf16 v[48:51], v[132:135], v[202:205], v[48:51]
	v_mfma_f32_16x16x32_bf16 v[40:43], v[140:143], v[202:205], v[40:43]
	v_mfma_f32_16x16x32_bf16 v[32:35], v[132:135], v[210:213], v[32:35]
	v_mfma_f32_16x16x32_bf16 v[24:27], v[140:143], v[210:213], v[24:27]
	v_mfma_f32_16x16x32_bf16 v[16:19], v[132:135], v[218:221], v[16:19]
	v_mfma_f32_16x16x32_bf16 v[8:11], v[140:143], v[218:221], v[8:11]
	s_setprio 0
	s_setprio 1
	v_mfma_f32_16x16x32_bf16 v[52:55], v[144:147], v[172:175], 0
	v_mfma_f32_16x16x32_bf16 v[44:47], v[164:167], v[172:175], 0
	v_mfma_f32_16x16x32_bf16 v[36:39], v[144:147], v[188:191], 0
	v_mfma_f32_16x16x32_bf16 v[28:31], v[164:167], v[188:191], 0
	v_mfma_f32_16x16x32_bf16 v[20:23], v[144:147], v[206:209], 0
	v_mfma_f32_16x16x32_bf16 v[12:15], v[164:167], v[206:209], 0
	v_mfma_f32_16x16x32_bf16 v[4:7], v[144:147], v[214:217], 0
	v_mfma_f32_16x16x32_bf16 v[0:3], v[164:167], v[214:217], 0
	v_mfma_f32_16x16x32_bf16 v[52:55], v[148:151], v[176:179], v[52:55]
	v_mfma_f32_16x16x32_bf16 v[44:47], v[168:171], v[176:179], v[44:47]
	v_mfma_f32_16x16x32_bf16 v[36:39], v[148:151], v[202:205], v[36:39]
	v_mfma_f32_16x16x32_bf16 v[28:31], v[168:171], v[202:205], v[28:31]
	v_mfma_f32_16x16x32_bf16 v[20:23], v[148:151], v[210:213], v[20:23]
	v_mfma_f32_16x16x32_bf16 v[12:15], v[168:171], v[210:213], v[12:15]
	v_mfma_f32_16x16x32_bf16 v[4:7], v[148:151], v[218:221], v[4:7]
	v_mfma_f32_16x16x32_bf16 v[0:3], v[168:171], v[218:221], v[0:3]
	s_setprio 0
	s_barrier
	s_add_i32 s91, 0, 0x18000
	s_add_i32 s92, 0, 0x1c000
	v_add_u32_e32 v140, s91, v183
	v_add_u32_e32 v168, s92, v183
	ds_read_b128 v[128:131], v140
	ds_read_b128 v[132:135], v140 offset:1024
	ds_read_b128 v[136:139], v140 offset:2048
	ds_read_b128 v[140:143], v140 offset:3072
	ds_read_b128 v[144:147], v168
	ds_read_b128 v[148:151], v168 offset:1024
	ds_read_b128 v[164:167], v168 offset:2048
	ds_read_b128 v[168:171], v168 offset:3072
	s_add_u32 s56, s56, 0x40000
	s_addc_u32 s57, s57, 0
	s_mov_b32 m0, s61
	v_lshl_add_u64 v[228:229], s[56:57], 0, v[156:157]
	ds_read_b128 v[172:175], v187 offset:32768
	ds_read_b128 v[176:179], v187 offset:33792
	ds_read_b128 v[188:191], v187 offset:34816
	ds_read_b128 v[202:205], v187 offset:35840
	ds_read_b128 v[206:209], v187 offset:36864
	ds_read_b128 v[210:213], v187 offset:37888
	ds_read_b128 v[214:217], v187 offset:38912
	ds_read_b128 v[218:221], v187 offset:39936
	global_load_lds_dwordx4 v[228:229], off
	v_lshl_add_u64 v[228:229], s[56:57], 0, v[154:155]
	s_mov_b32 m0, s82
	s_nop 0
	global_load_lds_dwordx4 v[228:229], off
	s_waitcnt vmcnt(8)
	s_waitcnt lgkmcnt(0)
	s_barrier
	s_setprio 1
	s_waitcnt lgkmcnt(0)
	v_mfma_f32_16x16x32_bf16 v[124:127], v[128:131], v[172:175], v[124:127]
	v_mfma_f32_16x16x32_bf16 v[120:123], v[136:139], v[172:175], v[120:123]
	v_mfma_f32_16x16x32_bf16 v[112:115], v[128:131], v[188:191], v[112:115]
	v_mfma_f32_16x16x32_bf16 v[104:107], v[136:139], v[188:191], v[104:107]
	v_mfma_f32_16x16x32_bf16 v[96:99], v[128:131], v[206:209], v[96:99]
	v_mfma_f32_16x16x32_bf16 v[88:91], v[136:139], v[206:209], v[88:91]
	v_mfma_f32_16x16x32_bf16 v[80:83], v[128:131], v[214:217], v[80:83]
	v_mfma_f32_16x16x32_bf16 v[72:75], v[136:139], v[214:217], v[72:75]
	v_mfma_f32_16x16x32_bf16 v[124:127], v[132:135], v[176:179], v[124:127]
	v_mfma_f32_16x16x32_bf16 v[120:123], v[140:143], v[176:179], v[120:123]
	v_mfma_f32_16x16x32_bf16 v[112:115], v[132:135], v[202:205], v[112:115]
	v_mfma_f32_16x16x32_bf16 v[104:107], v[140:143], v[202:205], v[104:107]
	v_mfma_f32_16x16x32_bf16 v[96:99], v[132:135], v[210:213], v[96:99]
	v_mfma_f32_16x16x32_bf16 v[88:91], v[140:143], v[210:213], v[88:91]
	v_mfma_f32_16x16x32_bf16 v[80:83], v[132:135], v[218:221], v[80:83]
	v_mfma_f32_16x16x32_bf16 v[72:75], v[140:143], v[218:221], v[72:75]
	s_setprio 0
	s_setprio 1
	v_mfma_f32_16x16x32_bf16 v[116:119], v[144:147], v[172:175], v[116:119]
	v_mfma_f32_16x16x32_bf16 v[108:111], v[164:167], v[172:175], v[108:111]
	v_mfma_f32_16x16x32_bf16 v[100:103], v[144:147], v[188:191], v[100:103]
	v_mfma_f32_16x16x32_bf16 v[92:95], v[164:167], v[188:191], v[92:95]
	v_mfma_f32_16x16x32_bf16 v[84:87], v[144:147], v[206:209], v[84:87]
	v_mfma_f32_16x16x32_bf16 v[76:79], v[164:167], v[206:209], v[76:79]
	v_mfma_f32_16x16x32_bf16 v[68:71], v[144:147], v[214:217], v[68:71]
	v_mfma_f32_16x16x32_bf16 v[64:67], v[164:167], v[214:217], v[64:67]
	v_mfma_f32_16x16x32_bf16 v[116:119], v[148:151], v[176:179], v[116:119]
	v_mfma_f32_16x16x32_bf16 v[108:111], v[168:171], v[176:179], v[108:111]
	v_mfma_f32_16x16x32_bf16 v[100:103], v[148:151], v[202:205], v[100:103]
	v_mfma_f32_16x16x32_bf16 v[92:95], v[168:171], v[202:205], v[92:95]
	v_mfma_f32_16x16x32_bf16 v[84:87], v[148:151], v[210:213], v[84:87]
	v_mfma_f32_16x16x32_bf16 v[76:79], v[168:171], v[210:213], v[76:79]
	v_mfma_f32_16x16x32_bf16 v[68:71], v[148:151], v[218:221], v[68:71]
	v_mfma_f32_16x16x32_bf16 v[64:67], v[168:171], v[218:221], v[64:67]
	s_setprio 0
	s_barrier
	s_add_i32 s56, s91, s54
	v_lshl_add_u64 v[184:185], v[184:185], 0, s[76:77]
	s_mov_b32 m0, s56
	ds_read_b128 v[172:175], v187 offset:49152
	ds_read_b128 v[176:179], v187 offset:50176
	ds_read_b128 v[188:191], v187 offset:51200
	ds_read_b128 v[202:205], v187 offset:52224
	ds_read_b128 v[206:209], v187 offset:53248
	ds_read_b128 v[210:213], v187 offset:54272
	ds_read_b128 v[214:217], v187 offset:55296
	ds_read_b128 v[218:221], v187 offset:56320
	global_load_lds_dwordx4 v[184:185], off
	s_add_i32 m0, s56, 0x2000
	s_add_u32 s38, s38, 0x40080
	v_lshl_add_u64 v[184:185], v[222:223], 0, s[76:77]
	s_addc_u32 s39, s39, 0
	s_add_i32 s56, s92, s54
	global_load_lds_dwordx4 v[184:185], off
	v_lshl_add_u64 v[184:185], s[38:39], 0, v[192:193]
	s_mov_b32 m0, s56
	s_nop 0
	global_load_lds_dwordx4 v[184:185], off
	v_lshl_add_u64 v[184:185], s[38:39], 0, v[152:153]
	s_add_i32 m0, s56, 0x2000
	s_nop 0
	global_load_lds_dwordx4 v[184:185], off
	v_lshl_add_u64 v[184:185], v[224:225], 0, s[76:77]
	s_mov_b32 m0, s68
	s_nop 0
	global_load_lds_dwordx4 v[184:185], off
	v_lshl_add_u64 v[184:185], v[226:227], 0, s[76:77]
	s_mov_b32 m0, s83
	s_nop 0
	global_load_lds_dwordx4 v[184:185], off
	s_waitcnt vmcnt(8)
	s_waitcnt lgkmcnt(0)
	s_barrier
	s_setprio 1
	s_waitcnt lgkmcnt(0)
	v_mfma_f32_16x16x32_bf16 v[60:63], v[128:131], v[172:175], v[60:63]
	v_mfma_f32_16x16x32_bf16 v[56:59], v[136:139], v[172:175], v[56:59]
	v_mfma_f32_16x16x32_bf16 v[48:51], v[128:131], v[188:191], v[48:51]
	v_mfma_f32_16x16x32_bf16 v[40:43], v[136:139], v[188:191], v[40:43]
	v_mfma_f32_16x16x32_bf16 v[32:35], v[128:131], v[206:209], v[32:35]
	v_mfma_f32_16x16x32_bf16 v[24:27], v[136:139], v[206:209], v[24:27]
	v_mfma_f32_16x16x32_bf16 v[16:19], v[128:131], v[214:217], v[16:19]
	v_mfma_f32_16x16x32_bf16 v[8:11], v[136:139], v[214:217], v[8:11]
	v_mfma_f32_16x16x32_bf16 v[60:63], v[132:135], v[176:179], v[60:63]
	v_mfma_f32_16x16x32_bf16 v[56:59], v[140:143], v[176:179], v[56:59]
	v_mfma_f32_16x16x32_bf16 v[48:51], v[132:135], v[202:205], v[48:51]
	v_mfma_f32_16x16x32_bf16 v[40:43], v[140:143], v[202:205], v[40:43]
	v_mfma_f32_16x16x32_bf16 v[32:35], v[132:135], v[210:213], v[32:35]
	v_mfma_f32_16x16x32_bf16 v[24:27], v[140:143], v[210:213], v[24:27]
	v_mfma_f32_16x16x32_bf16 v[16:19], v[132:135], v[218:221], v[16:19]
	v_mfma_f32_16x16x32_bf16 v[8:11], v[140:143], v[218:221], v[8:11]
	s_setprio 0
	s_setprio 1
	v_mfma_f32_16x16x32_bf16 v[52:55], v[144:147], v[172:175], v[52:55]
	v_mfma_f32_16x16x32_bf16 v[44:47], v[164:167], v[172:175], v[44:47]
	v_mfma_f32_16x16x32_bf16 v[36:39], v[144:147], v[188:191], v[36:39]
	v_mfma_f32_16x16x32_bf16 v[28:31], v[164:167], v[188:191], v[28:31]
	v_mfma_f32_16x16x32_bf16 v[20:23], v[144:147], v[206:209], v[20:23]
	v_mfma_f32_16x16x32_bf16 v[12:15], v[164:167], v[206:209], v[12:15]
	v_mfma_f32_16x16x32_bf16 v[4:7], v[144:147], v[214:217], v[4:7]
	v_mfma_f32_16x16x32_bf16 v[0:3], v[164:167], v[214:217], v[0:3]
	v_mfma_f32_16x16x32_bf16 v[52:55], v[148:151], v[176:179], v[52:55]
	v_mfma_f32_16x16x32_bf16 v[44:47], v[168:171], v[176:179], v[44:47]
	v_mfma_f32_16x16x32_bf16 v[36:39], v[148:151], v[202:205], v[36:39]
	v_mfma_f32_16x16x32_bf16 v[28:31], v[168:171], v[202:205], v[28:31]
	v_mfma_f32_16x16x32_bf16 v[20:23], v[148:151], v[210:213], v[20:23]
	v_mfma_f32_16x16x32_bf16 v[12:15], v[168:171], v[210:213], v[12:15]
	v_mfma_f32_16x16x32_bf16 v[4:7], v[148:151], v[218:221], v[4:7]
	v_mfma_f32_16x16x32_bf16 v[0:3], v[168:171], v[218:221], v[0:3]
	s_setprio 0
	s_barrier
	s_add_i32 s90, s90, 2
	s_add_u32 s88, s88, 0x100
	s_addc_u32 s89, s89, 0
	s_add_u32 s8, s8, 0x100
	s_addc_u32 s9, s9, 0
	s_cmp_gt_u32 s90, 13

.LBB0_932:
	s_mov_b64 s[86:87], s[26:27]
	s_mov_b64 s[88:89], s[8:9]
	s_add_u32 s56, s8, 0x100
	s_addc_u32 s57, s9, 0
	s_add_u32 s8, s26, 0x40080
	s_addc_u32 s9, s27, 0
	s_mov_b32 s60, -2
	s_add_u32 s26, s8, 0xfffc0080
	s_addc_u32 s27, s9, -1
	s_add_i32 s61, 0, 0x10000
	s_cmp_eq_u32 s60, 12
	s_cselect_b32 s29, s21, s27
	s_cselect_b32 s28, s54, s26
	s_cselect_b32 s27, s19, s57
	s_cselect_b32 s26, s55, s56
	s_add_i32 s68, 0, 0x14000
	v_add_u32_e32 v140, s61, v185
	v_add_u32_e32 v168, s68, v185
	ds_read_b128 v[128:131], v140
	ds_read_b128 v[132:135], v140 offset:1024
	ds_read_b128 v[136:139], v140 offset:2048
	ds_read_b128 v[140:143], v140 offset:3072
	ds_read_b128 v[144:147], v168
	ds_read_b128 v[148:151], v168 offset:1024
	ds_read_b128 v[164:167], v168 offset:2048
	ds_read_b128 v[168:171], v168 offset:3072
	v_lshl_add_u64 v[180:181], s[8:9], 0, v[162:163]
	s_add_i32 m0, s37, 0xc000
	ds_read_b128 v[172:175], v189
	ds_read_b128 v[176:179], v189 offset:1024
	ds_read_b128 v[202:205], v189 offset:2048
	ds_read_b128 v[206:209], v189 offset:3072
	ds_read_b128 v[210:213], v189 offset:4096
	ds_read_b128 v[214:217], v189 offset:5120
	ds_read_b128 v[218:221], v189 offset:6144
	ds_read_b128 v[222:225], v189 offset:7168
	global_load_lds_dwordx4 v[180:181], off
	v_lshl_add_u64 v[180:181], s[8:9], 0, v[160:161]
	s_add_i32 m0, s37, 0xe000
	s_nop 0
	global_load_lds_dwordx4 v[180:181], off
	s_add_i32 s49, s49, 1
	s_mul_i32 s6, s49, s43
	s_mul_hi_u32 s7, s49, s42
	s_add_i32 s7, s7, s6
	s_mul_i32 s6, s49, s42
	s_add_u32 s22, s6, s2
	s_addc_u32 s23, s7, s41
	v_cmp_gt_i64_e32 vcc, s[22:23], v[200:201]
	v_cmp_lt_i64_e64 s[6:7], s[22:23], v[198:199]
	s_cbranch_vccnz .LBB0_934
	s_ashr_i32 s18, s22, 31
	s_lshr_b32 s18, s18, 29
	s_add_i32 s18, s22, s18
	s_ashr_i32 s19, s18, 3
	s_and_b32 s18, s18, -8
	s_sub_i32 s18, s22, s18
	s_cmp_lt_i32 s18, 0
	s_movk_i32 s20, 0x2c1
	s_cselect_b32 s20, s20, 0x2c0
	s_mul_i32 s18, s18, s20
	s_add_i32 s18, s18, s19
	s_mul_hi_i32 s19, s18, 0x2e8ba2e9
	s_lshr_b32 s20, s19, 31
	s_ashr_i32 s19, s19, 5
	s_add_i32 s19, s19, s20
	s_lshl_b32 s20, s19, 3
	s_sub_i32 s21, 0x100, s20
	s_min_i32 s21, s21, 8
	s_abs_i32 s22, s21
	v_cvt_f32_u32_e32 v0, s22
	s_sub_i32 s24, 0, s22
	s_mulk_i32 s19, 0xb0
	s_sub_i32 s19, s18, s19
	v_rcp_iflag_f32_e32 v0, v0
	s_abs_i32 s18, s19
	s_xor_b32 s23, s19, s21
	s_ashr_i32 s23, s23, 31
	v_mul_f32_e32 v0, 0x4f7ffffe, v0
	v_cvt_u32_f32_e32 v0, v0
	s_nop 0
	v_readfirstlane_b32 s25, v0
	s_mul_i32 s24, s24, s25
	s_mul_hi_u32 s24, s25, s24
	s_add_i32 s25, s25, s24
	s_mul_hi_u32 s24, s18, s25
	s_mul_i32 s25, s24, s22
	s_sub_i32 s18, s18, s25
	s_add_i32 s32, s24, 1
	s_sub_i32 s25, s18, s22
	s_cmp_ge_u32 s18, s22
	s_cselect_b32 s24, s32, s24
	s_cselect_b32 s18, s25, s18
	s_add_i32 s25, s24, 1
	s_cmp_ge_u32 s18, s22
	s_cselect_b32 s18, s25, s24
	s_xor_b32 s18, s18, s23
	s_sub_i32 s18, s18, s23
	s_mul_i32 s21, s18, s21
	s_sub_i32 s19, s19, s21
	s_add_i32 s20, s20, s19
.LBB0_934:
	s_ashr_i32 s21, s20, 31
	s_lshl_b64 s[22:23], s[20:21], 19
	s_add_u32 s22, s30, s22
	s_addc_u32 s23, s31, s23
	s_and_b64 s[24:25], s[6:7], exec
	s_cselect_b32 s21, s23, s87
	s_cselect_b32 s54, s22, s86
	s_ashr_i32 s19, s18, 31
	s_lshl_b64 s[24:25], s[18:19], 19
	s_add_u32 s24, s34, s24
	s_addc_u32 s25, s35, s25
	s_and_b64 s[100:101], s[6:7], exec
	s_cselect_b32 s19, s25, s89
	s_cselect_b32 s55, s24, s88
	s_waitcnt vmcnt(8)
	s_waitcnt lgkmcnt(0)
	s_barrier
	s_setprio 1
	s_waitcnt lgkmcnt(0)
	v_mfma_f32_16x16x32_bf16 v[124:127], v[128:131], v[172:175], 0
	v_mfma_f32_16x16x32_bf16 v[116:119], v[136:139], v[172:175], 0
	v_mfma_f32_16x16x32_bf16 v[108:111], v[128:131], v[202:205], 0
	v_mfma_f32_16x16x32_bf16 v[100:103], v[136:139], v[202:205], 0
	v_mfma_f32_16x16x32_bf16 v[92:95], v[128:131], v[210:213], 0
	v_mfma_f32_16x16x32_bf16 v[84:87], v[136:139], v[210:213], 0
	v_mfma_f32_16x16x32_bf16 v[76:79], v[128:131], v[218:221], 0
	v_mfma_f32_16x16x32_bf16 v[68:71], v[136:139], v[218:221], 0
	v_mfma_f32_16x16x32_bf16 v[124:127], v[132:135], v[176:179], v[124:127]
	v_mfma_f32_16x16x32_bf16 v[116:119], v[140:143], v[176:179], v[116:119]
	v_mfma_f32_16x16x32_bf16 v[108:111], v[132:135], v[206:209], v[108:111]
	v_mfma_f32_16x16x32_bf16 v[100:103], v[140:143], v[206:209], v[100:103]
	v_mfma_f32_16x16x32_bf16 v[92:95], v[132:135], v[214:217], v[92:95]
	v_mfma_f32_16x16x32_bf16 v[84:87], v[140:143], v[214:217], v[84:87]
	v_mfma_f32_16x16x32_bf16 v[76:79], v[132:135], v[222:225], v[76:79]
	v_mfma_f32_16x16x32_bf16 v[68:71], v[140:143], v[222:225], v[68:71]
	s_setprio 0
	s_setprio 1
	v_mfma_f32_16x16x32_bf16 v[120:123], v[144:147], v[172:175], 0
	v_mfma_f32_16x16x32_bf16 v[112:115], v[164:167], v[172:175], 0
	v_mfma_f32_16x16x32_bf16 v[104:107], v[144:147], v[202:205], 0
	v_mfma_f32_16x16x32_bf16 v[96:99], v[164:167], v[202:205], 0
	v_mfma_f32_16x16x32_bf16 v[88:91], v[144:147], v[210:213], 0
	v_mfma_f32_16x16x32_bf16 v[80:83], v[164:167], v[210:213], 0
	v_mfma_f32_16x16x32_bf16 v[72:75], v[144:147], v[218:221], 0
	v_mfma_f32_16x16x32_bf16 v[64:67], v[164:167], v[218:221], 0
	v_mfma_f32_16x16x32_bf16 v[120:123], v[148:151], v[176:179], v[120:123]
	v_mfma_f32_16x16x32_bf16 v[112:115], v[168:171], v[176:179], v[112:115]
	v_mfma_f32_16x16x32_bf16 v[104:107], v[148:151], v[206:209], v[104:107]
	v_mfma_f32_16x16x32_bf16 v[96:99], v[168:171], v[206:209], v[96:99]
	v_mfma_f32_16x16x32_bf16 v[88:91], v[148:151], v[214:217], v[88:91]
	v_mfma_f32_16x16x32_bf16 v[80:83], v[168:171], v[214:217], v[80:83]
	v_mfma_f32_16x16x32_bf16 v[72:75], v[148:151], v[222:225], v[72:75]
	v_mfma_f32_16x16x32_bf16 v[64:67], v[168:171], v[222:225], v[64:67]
	s_setprio 0
	s_barrier
	s_add_i32 s61, s61, s36
	v_lshl_add_u64 v[180:181], s[26:27], 0, v[192:193]
	s_mov_b32 m0, s61
	ds_read_b128 v[172:175], v189 offset:16384
	ds_read_b128 v[176:179], v189 offset:17408
	ds_read_b128 v[202:205], v189 offset:18432
	ds_read_b128 v[206:209], v189 offset:19456
	ds_read_b128 v[210:213], v189 offset:20480
	ds_read_b128 v[214:217], v189 offset:21504
	ds_read_b128 v[218:221], v189 offset:22528
	ds_read_b128 v[222:225], v189 offset:23552
	global_load_lds_dwordx4 v[180:181], off
	s_add_i32 m0, s61, 0x2000
	s_add_u32 s82, s26, 0x40000
	v_lshl_add_u64 v[186:187], s[26:27], 0, v[152:153]
	s_addc_u32 s83, s27, 0
	s_add_i32 s61, s68, s36
	global_load_lds_dwordx4 v[186:187], off
	v_lshl_add_u64 v[190:191], s[82:83], 0, v[192:193]
	s_mov_b32 m0, s61
	v_lshl_add_u64 v[226:227], s[28:29], 0, v[154:155]
	global_load_lds_dwordx4 v[190:191], off
	v_lshl_add_u64 v[190:191], s[82:83], 0, v[152:153]
	s_add_i32 m0, s61, 0x2000
	s_nop 0
	global_load_lds_dwordx4 v[190:191], off
	v_lshl_add_u64 v[190:191], s[28:29], 0, v[156:157]
	s_mov_b32 m0, s37
	s_nop 0
	global_load_lds_dwordx4 v[190:191], off
	s_mov_b32 m0, s38
	s_nop 0
	global_load_lds_dwordx4 v[226:227], off
	s_waitcnt vmcnt(8)
	s_waitcnt lgkmcnt(0)
	s_barrier
	s_setprio 1
	s_waitcnt lgkmcnt(0)
	v_mfma_f32_16x16x32_bf16 v[60:63], v[128:131], v[172:175], 0
	v_mfma_f32_16x16x32_bf16 v[52:55], v[136:139], v[172:175], 0
	v_mfma_f32_16x16x32_bf16 v[44:47], v[128:131], v[202:205], 0
	v_mfma_f32_16x16x32_bf16 v[36:39], v[136:139], v[202:205], 0
	v_mfma_f32_16x16x32_bf16 v[28:31], v[128:131], v[210:213], 0
	v_mfma_f32_16x16x32_bf16 v[20:23], v[136:139], v[210:213], 0
	v_mfma_f32_16x16x32_bf16 v[12:15], v[128:131], v[218:221], 0
	v_mfma_f32_16x16x32_bf16 v[4:7], v[136:139], v[218:221], 0
	v_mfma_f32_16x16x32_bf16 v[60:63], v[132:135], v[176:179], v[60:63]
	v_mfma_f32_16x16x32_bf16 v[52:55], v[140:143], v[176:179], v[52:55]
	v_mfma_f32_16x16x32_bf16 v[44:47], v[132:135], v[206:209], v[44:47]
	v_mfma_f32_16x16x32_bf16 v[36:39], v[140:143], v[206:209], v[36:39]
	v_mfma_f32_16x16x32_bf16 v[28:31], v[132:135], v[214:217], v[28:31]
	v_mfma_f32_16x16x32_bf16 v[20:23], v[140:143], v[214:217], v[20:23]
	v_mfma_f32_16x16x32_bf16 v[12:15], v[132:135], v[222:225], v[12:15]
	v_mfma_f32_16x16x32_bf16 v[4:7], v[140:143], v[222:225], v[4:7]
	s_setprio 0
	s_setprio 1
	v_mfma_f32_16x16x32_bf16 v[56:59], v[144:147], v[172:175], 0
	v_mfma_f32_16x16x32_bf16 v[48:51], v[164:167], v[172:175], 0
	v_mfma_f32_16x16x32_bf16 v[40:43], v[144:147], v[202:205], 0
	v_mfma_f32_16x16x32_bf16 v[32:35], v[164:167], v[202:205], 0
	v_mfma_f32_16x16x32_bf16 v[24:27], v[144:147], v[210:213], 0
	v_mfma_f32_16x16x32_bf16 v[16:19], v[164:167], v[210:213], 0
	v_mfma_f32_16x16x32_bf16 v[8:11], v[144:147], v[218:221], 0
	v_mfma_f32_16x16x32_bf16 v[0:3], v[164:167], v[218:221], 0
	v_mfma_f32_16x16x32_bf16 v[56:59], v[148:151], v[176:179], v[56:59]
	v_mfma_f32_16x16x32_bf16 v[48:51], v[168:171], v[176:179], v[48:51]
	v_mfma_f32_16x16x32_bf16 v[40:43], v[148:151], v[206:209], v[40:43]
	v_mfma_f32_16x16x32_bf16 v[32:35], v[168:171], v[206:209], v[32:35]
	v_mfma_f32_16x16x32_bf16 v[24:27], v[148:151], v[214:217], v[24:27]
	v_mfma_f32_16x16x32_bf16 v[16:19], v[168:171], v[214:217], v[16:19]
	v_mfma_f32_16x16x32_bf16 v[8:11], v[148:151], v[222:225], v[8:11]
	v_mfma_f32_16x16x32_bf16 v[0:3], v[168:171], v[222:225], v[0:3]
	s_setprio 0
	s_barrier
	s_add_i32 s61, 0, 0x18000
	s_add_i32 s68, 0, 0x1c000
	v_add_u32_e32 v140, s61, v185
	v_add_u32_e32 v168, s68, v185
	ds_read_b128 v[128:131], v140
	ds_read_b128 v[132:135], v140 offset:1024
	ds_read_b128 v[136:139], v140 offset:2048
	ds_read_b128 v[140:143], v140 offset:3072
	ds_read_b128 v[144:147], v168
	ds_read_b128 v[148:151], v168 offset:1024
	ds_read_b128 v[164:167], v168 offset:2048
	ds_read_b128 v[168:171], v168 offset:3072
	s_add_u32 s28, s28, 0x40000
	s_addc_u32 s29, s29, 0
	s_mov_b32 m0, s39
	v_lshl_add_u64 v[228:229], s[28:29], 0, v[156:157]
	ds_read_b128 v[172:175], v189 offset:32768
	ds_read_b128 v[176:179], v189 offset:33792
	ds_read_b128 v[202:205], v189 offset:34816
	ds_read_b128 v[206:209], v189 offset:35840
	ds_read_b128 v[210:213], v189 offset:36864
	ds_read_b128 v[214:217], v189 offset:37888
	ds_read_b128 v[218:221], v189 offset:38912
	ds_read_b128 v[222:225], v189 offset:39936
	global_load_lds_dwordx4 v[228:229], off
	v_lshl_add_u64 v[228:229], s[28:29], 0, v[154:155]
	s_mov_b32 m0, s46
	s_nop 0
	global_load_lds_dwordx4 v[228:229], off
	s_waitcnt vmcnt(8)
	s_waitcnt lgkmcnt(0)
	s_barrier
	s_setprio 1
	s_waitcnt lgkmcnt(0)
	v_mfma_f32_16x16x32_bf16 v[124:127], v[128:131], v[172:175], v[124:127]
	v_mfma_f32_16x16x32_bf16 v[116:119], v[136:139], v[172:175], v[116:119]
	v_mfma_f32_16x16x32_bf16 v[108:111], v[128:131], v[202:205], v[108:111]
	v_mfma_f32_16x16x32_bf16 v[100:103], v[136:139], v[202:205], v[100:103]
	v_mfma_f32_16x16x32_bf16 v[92:95], v[128:131], v[210:213], v[92:95]
	v_mfma_f32_16x16x32_bf16 v[84:87], v[136:139], v[210:213], v[84:87]
	v_mfma_f32_16x16x32_bf16 v[76:79], v[128:131], v[218:221], v[76:79]
	v_mfma_f32_16x16x32_bf16 v[68:71], v[136:139], v[218:221], v[68:71]
	v_mfma_f32_16x16x32_bf16 v[124:127], v[132:135], v[176:179], v[124:127]
	v_mfma_f32_16x16x32_bf16 v[116:119], v[140:143], v[176:179], v[116:119]
	v_mfma_f32_16x16x32_bf16 v[108:111], v[132:135], v[206:209], v[108:111]
	v_mfma_f32_16x16x32_bf16 v[100:103], v[140:143], v[206:209], v[100:103]
	v_mfma_f32_16x16x32_bf16 v[92:95], v[132:135], v[214:217], v[92:95]
	v_mfma_f32_16x16x32_bf16 v[84:87], v[140:143], v[214:217], v[84:87]
	v_mfma_f32_16x16x32_bf16 v[76:79], v[132:135], v[222:225], v[76:79]
	v_mfma_f32_16x16x32_bf16 v[68:71], v[140:143], v[222:225], v[68:71]
	s_setprio 0
	s_setprio 1
	v_mfma_f32_16x16x32_bf16 v[120:123], v[144:147], v[172:175], v[120:123]
	v_mfma_f32_16x16x32_bf16 v[112:115], v[164:167], v[172:175], v[112:115]
	v_mfma_f32_16x16x32_bf16 v[104:107], v[144:147], v[202:205], v[104:107]
	v_mfma_f32_16x16x32_bf16 v[96:99], v[164:167], v[202:205], v[96:99]
	v_mfma_f32_16x16x32_bf16 v[88:91], v[144:147], v[210:213], v[88:91]
	v_mfma_f32_16x16x32_bf16 v[80:83], v[164:167], v[210:213], v[80:83]
	v_mfma_f32_16x16x32_bf16 v[72:75], v[144:147], v[218:221], v[72:75]
	v_mfma_f32_16x16x32_bf16 v[64:67], v[164:167], v[218:221], v[64:67]
	v_mfma_f32_16x16x32_bf16 v[120:123], v[148:151], v[176:179], v[120:123]
	v_mfma_f32_16x16x32_bf16 v[112:115], v[168:171], v[176:179], v[112:115]
	v_mfma_f32_16x16x32_bf16 v[104:107], v[148:151], v[206:209], v[104:107]
	v_mfma_f32_16x16x32_bf16 v[96:99], v[168:171], v[206:209], v[96:99]
	v_mfma_f32_16x16x32_bf16 v[88:91], v[148:151], v[214:217], v[88:91]
	v_mfma_f32_16x16x32_bf16 v[80:83], v[168:171], v[214:217], v[80:83]
	v_mfma_f32_16x16x32_bf16 v[72:75], v[148:151], v[222:225], v[72:75]
	v_mfma_f32_16x16x32_bf16 v[64:67], v[168:171], v[222:225], v[64:67]
	s_setprio 0
	s_barrier
	s_add_i32 s28, s61, s36
	v_lshl_add_u64 v[180:181], v[180:181], 0, s[76:77]
	s_mov_b32 m0, s28
	ds_read_b128 v[172:175], v189 offset:49152
	ds_read_b128 v[176:179], v189 offset:50176
	ds_read_b128 v[202:205], v189 offset:51200
	ds_read_b128 v[206:209], v189 offset:52224
	ds_read_b128 v[210:213], v189 offset:53248
	ds_read_b128 v[214:217], v189 offset:54272
	ds_read_b128 v[218:221], v189 offset:55296
	ds_read_b128 v[222:225], v189 offset:56320
	global_load_lds_dwordx4 v[180:181], off
	s_add_i32 m0, s28, 0x2000
	s_add_u32 s26, s26, 0x40080
	v_lshl_add_u64 v[180:181], v[186:187], 0, s[76:77]
	s_addc_u32 s27, s27, 0
	s_add_i32 s28, s68, s36
	global_load_lds_dwordx4 v[180:181], off
	v_lshl_add_u64 v[180:181], s[26:27], 0, v[192:193]
	s_mov_b32 m0, s28
	s_nop 0
	global_load_lds_dwordx4 v[180:181], off
	v_lshl_add_u64 v[180:181], s[26:27], 0, v[152:153]
	s_add_i32 m0, s28, 0x2000
	s_nop 0
	global_load_lds_dwordx4 v[180:181], off
	v_lshl_add_u64 v[180:181], v[190:191], 0, s[76:77]
	s_mov_b32 m0, s47
	s_nop 0
	global_load_lds_dwordx4 v[180:181], off
	v_lshl_add_u64 v[180:181], v[226:227], 0, s[76:77]
	s_mov_b32 m0, s48
	s_nop 0
	global_load_lds_dwordx4 v[180:181], off
	s_waitcnt vmcnt(8)
	s_waitcnt lgkmcnt(0)
	s_barrier
	s_setprio 1
	s_waitcnt lgkmcnt(0)
	v_mfma_f32_16x16x32_bf16 v[60:63], v[128:131], v[172:175], v[60:63]
	v_mfma_f32_16x16x32_bf16 v[52:55], v[136:139], v[172:175], v[52:55]
	v_mfma_f32_16x16x32_bf16 v[44:47], v[128:131], v[202:205], v[44:47]
	v_mfma_f32_16x16x32_bf16 v[36:39], v[136:139], v[202:205], v[36:39]
	v_mfma_f32_16x16x32_bf16 v[28:31], v[128:131], v[210:213], v[28:31]
	v_mfma_f32_16x16x32_bf16 v[20:23], v[136:139], v[210:213], v[20:23]
	v_mfma_f32_16x16x32_bf16 v[12:15], v[128:131], v[218:221], v[12:15]
	v_mfma_f32_16x16x32_bf16 v[4:7], v[136:139], v[218:221], v[4:7]
	v_mfma_f32_16x16x32_bf16 v[60:63], v[132:135], v[176:179], v[60:63]
	v_mfma_f32_16x16x32_bf16 v[52:55], v[140:143], v[176:179], v[52:55]
	v_mfma_f32_16x16x32_bf16 v[44:47], v[132:135], v[206:209], v[44:47]
	v_mfma_f32_16x16x32_bf16 v[36:39], v[140:143], v[206:209], v[36:39]
	v_mfma_f32_16x16x32_bf16 v[28:31], v[132:135], v[214:217], v[28:31]
	v_mfma_f32_16x16x32_bf16 v[20:23], v[140:143], v[214:217], v[20:23]
	v_mfma_f32_16x16x32_bf16 v[12:15], v[132:135], v[222:225], v[12:15]
	v_mfma_f32_16x16x32_bf16 v[4:7], v[140:143], v[222:225], v[4:7]
	s_setprio 0
	s_setprio 1
	v_mfma_f32_16x16x32_bf16 v[56:59], v[144:147], v[172:175], v[56:59]
	v_mfma_f32_16x16x32_bf16 v[48:51], v[164:167], v[172:175], v[48:51]
	v_mfma_f32_16x16x32_bf16 v[40:43], v[144:147], v[202:205], v[40:43]
	v_mfma_f32_16x16x32_bf16 v[32:35], v[164:167], v[202:205], v[32:35]
	v_mfma_f32_16x16x32_bf16 v[24:27], v[144:147], v[210:213], v[24:27]
	v_mfma_f32_16x16x32_bf16 v[16:19], v[164:167], v[210:213], v[16:19]
	v_mfma_f32_16x16x32_bf16 v[8:11], v[144:147], v[218:221], v[8:11]
	v_mfma_f32_16x16x32_bf16 v[0:3], v[164:167], v[218:221], v[0:3]
	v_mfma_f32_16x16x32_bf16 v[56:59], v[148:151], v[176:179], v[56:59]
	v_mfma_f32_16x16x32_bf16 v[48:51], v[168:171], v[176:179], v[48:51]
	v_mfma_f32_16x16x32_bf16 v[40:43], v[148:151], v[206:209], v[40:43]
	v_mfma_f32_16x16x32_bf16 v[32:35], v[168:171], v[206:209], v[32:35]
	v_mfma_f32_16x16x32_bf16 v[24:27], v[148:151], v[214:217], v[24:27]
	v_mfma_f32_16x16x32_bf16 v[16:19], v[168:171], v[214:217], v[16:19]
	v_mfma_f32_16x16x32_bf16 v[8:11], v[148:151], v[222:225], v[8:11]
	v_mfma_f32_16x16x32_bf16 v[0:3], v[168:171], v[222:225], v[0:3]
	s_setprio 0
	s_barrier
	s_add_i32 s60, s60, 2
	s_add_u32 s56, s56, 0x100
	s_addc_u32 s57, s57, 0
	s_add_u32 s8, s8, 0x100
	s_addc_u32 s9, s9, 0
	s_cmp_gt_u32 s60, 13
